# MLA unit prologue: six Q-tile loads and first K/V tile issued together, LDS writes behind counted waits (was one load per wait)
# baseline (speedup 1.0000x reference)
; #define LAS __attribute__((address_space(3)))
; #define LOADT(RK, RV, tt) do { const char* kb_ = (const char*)(Kb + (size_t)(tt) * (64 * 192)); const char* vb_ = (const char*)(Vb + (size_t)(tt) * 64); \
;     _Pragma("unroll") for (int i = 0; i < 3; ++i) RK[i] = *(const u32x4*)(kb_ + i * 8192 + kgo); \
;     _Pragma("unroll") for (int i = 0; i < 2; ++i) RV[i] = *(const u32x4*)(vb_ + (size_t)i * (64 * S * 2) + vgo); } while (0)
; #define STORET(RK, RV, kbuf, vbuf) do { \
;     _Pragma("unroll") for (int i = 0; i < 3; ++i) *(LAS u32x4*)(L + (kbuf) * (2 * MLA_KS) + kds[i]) = RK[i]; \
;     _Pragma("unroll") for (int i = 0; i < 2; ++i) { LAS u32x2* d_ = (LAS u32x2*)(L + (vbuf) * (2 * MLA_VS) + vds + i * (64 * 36)); d_[0] = (u32x2){RV[i].x, RV[i].y}; d_[1] = (u32x2){RV[i].z, RV[i].w}; } } while (0)
; __device__ __forceinline__ void mla_unit(LAS unsigned char* lds, int bh, int x, const bf16* QM, const bf16* KM, const bf16* VMT, bf16* OUT, ssq_t* SSo, int tid, int lane, int wave) {
;     ...
;     {
;         const bf16* Qb = QM + ((size_t)bh * S + q0) * 192;
; #pragma unroll
;         for (int i = 0; i < 6; ++i) { const int c = tid + 512 * i, row = c / 24, ch = c - 24 * row;
;             *(LAS u32x4*)(Qs + row * 200 + ch * 8) = *(const u32x4*)(Qb + (size_t)c * 8); }
;     }
;     LOADT(rk0, rv0, 0); STORET(rk0, rv0, 0, 0);
;     LOADT(rk1, rv1, 1);
;     if (T > 2) LOADT(rk0, rv0, 2);
.LBB0_1285:
	s_and_b32 s4, s41, 31
	s_bfe_u32 s46, s41, 0x30005
	s_xor_b32 s8, s4, 63
	s_cmpk_lt_u32 s41, 0x100
	s_cselect_b32 s4, s8, s4
	s_lshl_b32 s47, s4, 7
	s_lshl_b32 s8, s46, 13
	s_or_b32 s8, s8, s47
	s_lshl_b32 s18, s46, 21
	s_mulk_i32 s8, 0x180
	s_add_u32 s8, s13, s8
	s_addc_u32 s9, s34, 0
	v_lshl_add_u64 v[2:3], s[8:9], 0, v[166:167]
	global_load_dwordx4 v[10:13], v[2:3], off
	s_mul_i32 s10, s46, 0x300000
	s_movk_i32 s1, 0x2000
	v_add_u32_e32 v1, 0xc800, v214
	v_lshl_add_u64 v[2:3], s[8:9], 0, v[168:169]
	global_load_dwordx4 v[14:17], v[2:3], off
	v_lshl_add_u64 v[2:3], s[8:9], 0, v[170:171]
	global_load_dwordx4 v[18:21], v[2:3], off
	v_lshl_add_u64 v[2:3], s[8:9], 0, v[172:173]
	global_load_dwordx4 v[22:25], v[2:3], off
	v_lshl_add_u64 v[2:3], s[8:9], 0, v[174:175]
	global_load_dwordx4 v[26:29], v[2:3], off
	v_lshl_add_u64 v[2:3], s[8:9], 0, v[176:177]
	global_load_dwordx4 v[30:33], v[2:3], off
	s_add_u32 s8, s35, s10
	s_addc_u32 s9, s36, 0
	s_cmp_lg_u32 s4, 0
	v_lshl_add_u64 v[2:3], s[8:9], 0, v[178:179]
	v_add_co_u32_e32 v4, vcc, s1, v2
	s_movk_i32 s1, 0x4000
	s_nop 0
	v_addc_co_u32_e32 v5, vcc, 0, v3, vcc
	global_load_dwordx4 v[124:127], v[2:3], off
	global_load_dwordx4 v[128:131], v[4:5], off
	v_add_co_u32_e32 v4, vcc, s1, v2
	s_mov_b32 s8, 0x100000
	s_nop 0
	v_addc_co_u32_e32 v5, vcc, 0, v3, vcc
	global_load_dwordx4 v[132:135], v[4:5], off
	v_lshl_add_u64 v[4:5], v[180:181], 0, s[18:19]
	v_add_co_u32_e32 v6, vcc, s8, v4
	global_load_dwordx4 v[136:139], v[4:5], off
	s_nop 0
	v_addc_co_u32_e32 v7, vcc, 0, v5, vcc
	global_load_dwordx4 v[144:147], v[6:7], off
	s_movk_i32 s1, 0x6000
	v_add_co_u32_e32 v8, vcc, s1, v2
	s_cselect_b64 s[8:9], -1, 0
	s_nop 0
	v_addc_co_u32_e32 v9, vcc, 0, v3, vcc
	s_cmp_eq_u32 s4, 0
	s_waitcnt vmcnt(10)
	ds_write_b128 v217, v[10:13]
	s_waitcnt vmcnt(9)
	ds_write_b128 v218, v[14:17]
	s_waitcnt vmcnt(8)
	ds_write_b128 v219, v[18:21]
	s_waitcnt vmcnt(7)
	ds_write_b128 v220, v[22:25]
	s_waitcnt vmcnt(6)
	ds_write_b128 v221, v[26:29]
	s_waitcnt vmcnt(5)
	ds_write_b128 v222, v[30:33]
	s_waitcnt vmcnt(4)
	ds_write_b128 v211, v[124:127]
	s_waitcnt vmcnt(3)
	ds_write_b128 v212, v[128:131]
	s_waitcnt vmcnt(2)
	ds_write_b128 v213, v[132:135]
	global_load_dwordx4 v[140:143], v[8:9], off
	v_add_co_u32_e32 v8, vcc, 0x8000, v2
	s_waitcnt vmcnt(2)
	ds_write2_b64 v1, v[136:137], v[138:139] offset1:1
	v_addc_co_u32_e32 v9, vcc, 0, v3, vcc
	v_add_u32_e32 v1, 0xda00, v214
	global_load_dwordx4 v[148:151], v[8:9], off
	v_add_co_u32_e32 v8, vcc, 0xa000, v2
	s_waitcnt vmcnt(2)
	ds_write2_b64 v1, v[144:145], v[146:147] offset1:1
	v_addc_co_u32_e32 v9, vcc, 0, v3, vcc
	global_load_dwordx4 v[152:155], v[8:9], off
	global_load_dwordx4 v[156:159], v[4:5], off offset:128
	global_load_dwordx4 v[160:163], v[6:7], off offset:128
	s_cbranch_scc1 .LBB0_1287
	v_add_co_u32_e32 v6, vcc, 0xc000, v2
	s_nop 1
	v_addc_co_u32_e32 v7, vcc, 0, v3, vcc
	v_add_co_u32_e32 v8, vcc, 0xe000, v2
	s_nop 1
	v_addc_co_u32_e32 v9, vcc, 0, v3, vcc
	v_add_co_u32_e32 v10, vcc, 0x10000, v2
	s_nop 1
	v_addc_co_u32_e32 v11, vcc, 0, v3, vcc
	global_load_dwordx4 v[128:131], v[8:9], off
	global_load_dwordx4 v[132:135], v[10:11], off
	global_load_dwordx4 v[124:127], v[6:7], off
	global_load_dwordx4 v[136:139], v[4:5], off offset:256
	v_add_co_u32_e32 v6, vcc, 0x100000, v4
	s_nop 1
	v_addc_co_u32_e32 v7, vcc, 0, v5, vcc
	global_load_dwordx4 v[144:147], v[6:7], off offset:256
